# stack6 plus 156 canonicalizing v_max (x,x) removed in the relu-squared epilogue and attention, with s_nop padding for the store-data hazard
# baseline (speedup 1.0000x reference)
; #define MFMA32(a, b, c) __builtin_amdgcn_mfma_f32_32x32x16_bf16((a), (b), (c), 0, 0, 0)
; __device__ __forceinline__ void attn_unit(const bf16* Q, const bf16* Kb, const bf16* VT, bf16* OSB, int wu, int lane) {
;     const int h = wu & 7, blk = wu >> 3, qblk = blk & 255, b = blk >> 8;
;     const int r = lane & 31, hh = lane >> 5;
;     const int pr = (r & 19) | ((r & 8) >> 1) | ((r & 4) << 1);
;     const size_t tok0 = (size_t)b * SEQ + (size_t)qblk * 32;
;     bf16x8 qf[4];
;     { const bf16* qp = Q + (tok0 + r) * 512 + h * 64 + 8 * hh;
; #pragma unroll
;       for (int kk = 0; kk < 4; ++kk) qf[kk] = *(const bf16x8*)(qp + kk * 16); }
;     const bf16* kbase = Kb + ((size_t)b * SEQ + pr) * 512 + h * 64 + 8 * hh;
;     const bf16* vbase = VT + ((size_t)b * (SEQ / 32) * 512 + h * 64 + r) * 32 + 8 * hh;
;     bf16x8 kf[4], vf[2][2];
;     { const bf16* kp = kbase + (size_t)qblk * 32 * 512; const bf16* vp = vbase + (size_t)qblk * (512 * 32);
; #pragma unroll
;       for (int kk = 0; kk < 4; ++kk) kf[kk] = *(const bf16x8*)(kp + kk * 16);
; #pragma unroll
;       for (int mt = 0; mt < 2; ++mt)
; #pragma unroll
;           for (int s = 0; s < 2; ++s) vf[mt][s] = *(const bf16x8*)(vp + mt * 32 * 32 + 16 * s); }
;     f32x16 o0, o1;
; #pragma unroll
;     for (int i = 0; i < 16; ++i) { o0[i] = 0.f; o1[i] = 0.f; }
;     float carry = 0.f;
;     ...
;         bf16x8 kn[4], vn[2][2];
;         { const int ktn = kt > 0 ? kt - 1 : 0; const bf16* kp = kbase + (size_t)ktn * 32 * 512; const bf16* vp = vbase + (size_t)ktn * (512 * 32);
; #pragma unroll
;           for (int kk = 0; kk < 4; ++kk) kn[kk] = *(const bf16x8*)(kp + kk * 16);
; #pragma unroll
;           for (int mt = 0; mt < 2; ++mt)
; #pragma unroll
;               for (int s = 0; s < 2; ++s) vn[mt][s] = *(const bf16x8*)(vp + mt * 32 * 32 + 16 * s); }
;         f32x16 sc;
; #pragma unroll
;         for (int i = 0; i < 16; ++i) sc[i] = 0.f;
; #pragma unroll
;         for (int kk = 0; kk < 4; ++kk) sc = MFMA32(kf[kk], qf[kk], sc);
.LBB0_115:
	s_and_b64 vcc, exec, s[46:47]
	s_cbranch_vccz .LBB0_110
	s_ashr_i32 s56, s96, 11
	s_bfe_u32 s42, s96, 0x50006
	s_lshl_b32 s42, s42, 3
	s_and_b32 s41, s96, 7
	s_or_b32 s42, s42, s41
	s_ashr_i32 s57, s56, 31
	s_lshl_b64 s[64:65], s[56:57], 13
	s_lshl_b32 s41, s42, 5
	s_or_b32 s41, s64, s41
	v_or_b32_e32 v96, s41, v86
	s_lshl_b32 s41, s96, 3
	v_mov_b32_e32 v1, s65
	v_or_b32_e32 v0, s64, v76
	v_readlane_b32 s58, v253, 8
	s_and_b32 s41, s41, 0x1c0
	v_lshlrev_b64 v[0:1], 10, v[0:1]
	v_readlane_b32 s59, v253, 9
	s_lshl_b32 s46, s41, 1
	s_mov_b32 s47, s95
	v_lshl_add_u64 v[0:1], s[58:59], 0, v[0:1]
	v_mov_b32_e32 v95, v179
	v_lshl_add_u64 v[0:1], v[0:1], 0, s[46:47]
	v_lshl_add_u64 v[98:99], v[0:1], 0, v[94:95]
	s_lshl_b32 s94, s42, 15
	v_lshl_add_u64 v[6:7], v[98:99], 0, s[94:95]
	global_load_dwordx4 v[0:3], v[6:7], off
	v_mov_b32_e32 v97, s65
	v_lshlrev_b64 v[4:5], 10, v[96:97]
	v_lshl_add_u64 v[4:5], s[92:93], 0, v[4:5]
	v_lshl_add_u64 v[4:5], v[4:5], 0, s[46:47]
	v_lshl_add_u64 v[28:29], v[4:5], 0, v[94:95]
	global_load_dwordx4 v[48:51], v[28:29], off
	global_load_dwordx4 v[16:19], v[6:7], off offset:32
	global_load_dwordx4 v[52:55], v[28:29], off offset:32
	global_load_dwordx4 v[20:23], v[6:7], off offset:64
	global_load_dwordx4 v[56:59], v[28:29], off offset:64
	global_load_dwordx4 v[24:27], v[6:7], off offset:96
	global_load_dwordx4 v[60:63], v[28:29], off offset:96
	v_xor_b32_e32 v28, 32, v226
	s_lshl_b64 s[56:57], s[56:57], 17
	s_or_b32 s41, s56, s41
	s_waitcnt vmcnt(0)
	v_mfma_f32_32x32x16_bf16 v[0:15], v[0:3], v[48:51], 0
	s_waitcnt vmcnt(4)
	v_mfma_f32_32x32x16_bf16 v[0:15], v[16:19], v[52:55], v[0:15]
	v_and_b32_e32 v16, 64, v226
	v_add_u32_e32 v16, 64, v16
	v_cmp_lt_i32_e32 vcc, v28, v16
	v_mov_b32_e32 v17, s57
	s_nop 0
	v_cndmask_b32_e32 v16, v226, v28, vcc
	v_lshlrev_b32_e32 v73, 2, v16
	s_waitcnt vmcnt(2)
	v_mfma_f32_32x32x16_bf16 v[0:15], v[20:23], v[56:59], v[0:15]
	v_or_b32_e32 v16, s41, v86
	v_lshlrev_b64 v[16:17], 6, v[16:17]
	v_lshl_add_u64 v[100:101], v[78:79], 0, v[16:17]
	v_lshl_add_u64 v[36:37], v[100:101], 0, s[94:95]
	global_load_dwordx4 v[16:19], v[36:37], off
	global_load_dwordx4 v[32:35], v[36:37], off offset:32
	global_load_dwordx4 v[148:151], v[36:37], off offset:2048
	global_load_dwordx4 v[152:155], v[36:37], off offset:2080
	s_sub_i32 s56, s94, 0x8000
	s_max_i32 s56, s56, 0
	s_mov_b32 s57, 0
	v_lshl_add_u64 v[156:157], v[98:99], 0, s[56:57]
	v_lshl_add_u64 v[158:159], v[100:101], 0, s[56:57]
	global_load_dwordx4 v[192:195], v[156:157], off
	global_load_dwordx4 v[196:199], v[156:157], off offset:32
	global_load_dwordx4 v[200:203], v[156:157], off offset:64
	global_load_dwordx4 v[204:207], v[156:157], off offset:96
	global_load_dwordx4 v[208:211], v[158:159], off
	global_load_dwordx4 v[212:215], v[158:159], off offset:32
	global_load_dwordx4 v[216:219], v[158:159], off offset:2048
	global_load_dwordx4 v[220:223], v[158:159], off offset:2080
	s_waitcnt vmcnt(12)
; #define MFMA32(a, b, c) __builtin_amdgcn_mfma_f32_32x32x16_bf16((a), (b), (c), 0, 0, 0)
; __device__ __forceinline__ void attn_unit(const bf16* Q, const bf16* Kb, const bf16* VT, bf16* OSB, int wu, int lane) {
;     ...
;         const int lim = (kt == qblk) ? r : 64;
;         float ln[16], ls[16];
; #pragma unroll
;         for (int i = 0; i < 16; ++i) {
;             const float z = sc[i];
;             const float l2 = __builtin_amdgcn_logf(1.0f + __builtin_amdgcn_exp2f(-fabsf(z)));
;             const float sp = fmaxf(z, 0.f) + l2;
;             const bool valid = (16 * (i >> 3) + 8 * hh + (i & 7)) < lim;
;             ln[i] = valid ? -sp : 0.f;
;             ls[i] = valid ? z - sp : -1e30f;
;         }
;         float ex[16], gs[2];
; #pragma unroll
;         for (int s = 0; s < 2; ++s) { float run = 0.f;
; #pragma unroll
;             for (int j = 7; j >= 0; --j) { ex[8 * s + j] = run; run += ln[8 * s + j]; }
;             gs[s] = run; }
;         const float pg0 = __shfl_xor(gs[0], 32), pg1 = __shfl_xor(gs[1], 32);
;         const float off1 = (hh == 0 ? pg1 : 0.f) + carry;
;         const float off0 = gs[1] + pg1 + (hh == 0 ? pg0 : 0.f) + carry;
;         float a0[8], a1[8];
; #pragma unroll
;         for (int j = 0; j < 8; ++j) { a0[j] = __builtin_amdgcn_exp2f(ls[j] + ex[j] + off0); a1[j] = __builtin_amdgcn_exp2f(ls[8 + j] + ex[8 + j] + off1); }
;         const bf16x8 p0 = pack8(a0), p1 = pack8(a1);
;         o0 = MFMA32(vf[0][0], p0, o0); o0 = MFMA32(vf[0][1], p1, o0);
;         o1 = MFMA32(vf[1][0], p0, o1); o1 = MFMA32(vf[1][1], p1, o1);
;         carry += (gs[0] + gs[1]) + (pg0 + pg1);
;         if (__all(carry < -60.f)) break;
	v_mfma_f32_32x32x16_bf16 v[0:15], v[24:27], v[60:63], v[0:15]
	s_nop 11
	v_exp_f32_e64 v20, -|v0|
	v_exp_f32_e64 v22, -|v1|
	v_exp_f32_e64 v24, -|v2|
	v_exp_f32_e64 v26, -|v3|
	v_exp_f32_e64 v28, -|v4|
	v_exp_f32_e64 v30, -|v5|
	v_exp_f32_e64 v38, -|v6|
	v_exp_f32_e64 v42, -|v8|
	v_add_f32_e32 v20, 1.0, v20
	v_add_f32_e32 v22, 1.0, v22
	v_add_f32_e32 v24, 1.0, v24
	v_add_f32_e32 v26, 1.0, v26
	v_add_f32_e32 v28, 1.0, v28
	v_add_f32_e32 v30, 1.0, v30
	v_add_f32_e32 v38, 1.0, v38
	v_add_f32_e32 v42, 1.0, v42
	v_log_f32_e32 v20, v20
	v_log_f32_e32 v22, v22
	v_log_f32_e32 v24, v24
	v_log_f32_e32 v26, v26
	v_log_f32_e32 v28, v28
	v_log_f32_e32 v30, v30
	v_log_f32_e32 v38, v38
	v_log_f32_e32 v42, v42
	v_exp_f32_e64 v44, -|v9|
	v_max_f32_e32 v21, 0, v0
	v_max_f32_e32 v23, 0, v1
	v_max_f32_e32 v25, 0, v2
	v_max_f32_e32 v27, 0, v3
	v_max_f32_e32 v29, 0, v4
	v_max_f32_e32 v31, 0, v5
	v_max_f32_e32 v39, 0, v6
	v_max_f32_e32 v43, 0, v8
	v_add_f32_e32 v20, v21, v20
	v_add_f32_e32 v21, v23, v22
	v_add_f32_e32 v22, v25, v24
	v_add_f32_e32 v23, v27, v26
	v_add_f32_e32 v24, v29, v28
	v_add_f32_e32 v25, v31, v30
	v_add_f32_e32 v26, v39, v38
	v_add_f32_e32 v28, v43, v42
	v_sub_f32_e32 v0, v0, v20
	v_add_f32_e32 v44, 1.0, v44
	v_cndmask_b32_e64 v30, 0, -v20, s[6:7]
	v_cndmask_b32_e64 v20, 0, -v21, s[8:9]
	v_sub_f32_e32 v1, v1, v21
	v_cndmask_b32_e64 v21, 0, -v22, s[10:11]
	v_sub_f32_e32 v2, v2, v22
	v_cndmask_b32_e64 v22, 0, -v23, s[12:13]
	v_sub_f32_e32 v3, v3, v23
	v_cndmask_b32_e64 v23, 0, -v24, s[14:15]
	v_sub_f32_e32 v4, v4, v24
	v_cndmask_b32_e64 v24, 0, -v25, s[16:17]
	v_sub_f32_e32 v5, v5, v25
	v_cndmask_b32_e64 v25, 0, -v26, s[18:19]
	v_sub_f32_e32 v6, v6, v26
	v_cndmask_b32_e64 v26, 0, -v28, s[22:23]
	v_sub_f32_e32 v8, v8, v28
	v_cndmask_b32_e64 v28, v228, v0, s[6:7]
	v_exp_f32_e64 v0, -|v10|
	v_log_f32_e32 v44, v44
	v_max_f32_e32 v45, 0, v9
	v_add_f32_e32 v0, 1.0, v0
	v_add_f32_e32 v29, v45, v44
	v_log_f32_e32 v0, v0
	v_cndmask_b32_e64 v31, v228, v1, s[8:9]
	v_cndmask_b32_e64 v178, v228, v6, s[18:19]
	v_cndmask_b32_e64 v6, v228, v8, s[22:23]
	v_cndmask_b32_e64 v1, 0, -v29, s[24:25]
	v_sub_f32_e32 v8, v9, v29
	v_exp_f32_e64 v29, -|v11|
	v_max_f32_e32 v9, 0, v10
	v_add_f32_e32 v0, v9, v0
	v_cndmask_b32_e64 v9, 0, -v0, s[26:27]
	v_sub_f32_e32 v0, v10, v0
	v_add_f32_e32 v10, 1.0, v29
	v_log_f32_e32 v10, v10
	v_cndmask_b32_e64 v29, v228, v0, s[26:27]
	v_max_f32_e32 v0, 0, v11
	v_add_f32_e32 v0, v0, v10
	v_exp_f32_e64 v10, -|v12|
	v_cndmask_b32_e64 v38, 0, -v0, s[28:29]
	v_sub_f32_e32 v0, v11, v0
	v_cndmask_b32_e64 v11, v228, v0, s[28:29]
	v_add_f32_e32 v0, 1.0, v10
	v_log_f32_e32 v0, v0
	v_exp_f32_e64 v39, -|v13|
	v_max_f32_e32 v10, 0, v12
	v_exp_f32_e64 v40, -|v7|
	v_add_f32_e32 v0, v10, v0
	v_cndmask_b32_e64 v10, 0, -v0, s[30:31]
	v_sub_f32_e32 v0, v12, v0
	v_add_f32_e32 v12, 1.0, v39
	v_log_f32_e32 v12, v12
	v_add_f32_e32 v40, 1.0, v40
	v_cndmask_b32_e64 v39, v228, v0, s[30:31]
	v_log_f32_e32 v40, v40
	v_max_f32_e32 v0, 0, v13
	v_add_f32_e32 v0, v0, v12
	v_exp_f32_e64 v12, -|v14|
	v_max_f32_e32 v41, 0, v7
	v_add_f32_e32 v27, v41, v40
	v_cndmask_b32_e64 v40, 0, -v0, s[34:35]
	v_sub_f32_e32 v0, v13, v0
	v_cndmask_b32_e64 v13, v228, v0, s[34:35]
	v_add_f32_e32 v0, 1.0, v12
	v_log_f32_e32 v0, v0
	v_exp_f32_e64 v41, -|v15|
	v_max_f32_e32 v12, 0, v14
	v_add_f32_e32 v0, v12, v0
	v_cndmask_b32_e64 v12, 0, -v0, s[36:37]
	v_sub_f32_e32 v0, v14, v0
	v_add_f32_e32 v14, 1.0, v41
	v_log_f32_e32 v14, v14
	v_cndmask_b32_e64 v41, v228, v0, s[36:37]
	v_max_f32_e32 v0, 0, v15
	v_add_f32_e32 v14, v0, v14
	v_sub_f32_e32 v7, v7, v27
	v_sub_f32_e32 v0, 0, v27
	v_sub_f32_e32 v27, 0, v14
	v_cndmask_b32_e64 v27, 0, v27, s[38:39]
	v_cndmask_b32_e64 v0, 0, v0, s[20:21]
	v_add_f32_e32 v12, v12, v27
	v_add_f32_e32 v25, v25, v0
	v_add_f32_e32 v40, v40, v12
	v_add_f32_e32 v24, v24, v25
	v_add_f32_e32 v10, v10, v40
	v_add_f32_e32 v23, v23, v24
	v_add_f32_e32 v38, v38, v10
	v_add_f32_e32 v22, v22, v23
	v_add_f32_e32 v9, v9, v38
	v_add_f32_e32 v21, v21, v22
	v_add_f32_e32 v46, v1, v9
	v_add_f32_e32 v43, v26, v46
	v_add_f32_e32 v20, v20, v21
	ds_bpermute_b32 v42, v73, v43
	v_add_f32_e32 v45, v30, v20
	ds_bpermute_b32 v44, v73, v45
	v_sub_f32_e32 v14, v15, v14
	v_cndmask_b32_e64 v2, v228, v2, s[10:11]
	s_waitcnt lgkmcnt(0)
	v_add_f32_e32 v1, 0, v42
	v_cndmask_b32_e64 v15, v1, 0, s[4:5]
	v_add_f32_e32 v1, v43, v42
	s_waitcnt lgkmcnt(0)
	v_cndmask_b32_e64 v26, v44, 0, s[4:5]
	v_cndmask_b32_e64 v3, v228, v3, s[12:13]
	v_cndmask_b32_e64 v4, v228, v4, s[14:15]
	v_cndmask_b32_e64 v5, v228, v5, s[16:17]
	v_add_f32_e32 v1, v26, v1
	v_add_f32_e32 v2, v2, v22
	v_add_f32_e32 v3, v3, v23
	v_add_f32_e32 v4, v4, v24
	v_add_f32_e32 v5, v5, v25
	v_pk_add_f32 v[0:1], v[0:1], v[178:179]
	v_add_f32_e32 v20, v28, v20
	v_add_f32_e32 v21, v31, v21
	v_add_f32_e32 v2, v2, v1
	v_add_f32_e32 v3, v3, v1
	v_add_f32_e32 v4, v4, v1
	v_add_f32_e32 v5, v5, v1
	v_add_f32_e32 v0, v0, v1
	v_add_f32_e32 v12, v13, v12
	v_add_f32_e32 v13, v20, v1
	v_add_f32_e32 v20, v21, v1
	v_exp_f32_e32 v2, v2
	v_exp_f32_e32 v3, v3
	v_exp_f32_e32 v4, v4
	v_exp_f32_e32 v5, v5
	v_exp_f32_e32 v21, v0
	v_add_f32_e32 v0, v27, v41
	v_add_f32_e32 v0, v15, v0
	v_exp_f32_e32 v41, v0
	v_add_f32_e32 v0, 0, v7
	v_cndmask_b32_e64 v8, v228, v8, s[24:25]
	v_cndmask_b32_e64 v0, v228, v0, s[20:21]
	v_add_f32_e32 v14, 0, v14
	v_add_f32_e32 v6, v6, v46
	v_add_f32_e32 v8, v8, v9
	v_add_f32_e32 v0, v0, v1
	v_cvt_pk_bf16_f32 v1, v2, v3
	v_cvt_pk_bf16_f32 v2, v4, v5
	v_cndmask_b32_e64 v4, v228, v14, s[38:39]
	v_add_f32_e32 v6, v15, v6
	v_add_f32_e32 v8, v15, v8
	v_exp_f32_e32 v13, v13
	v_exp_f32_e32 v20, v20
	v_exp_f32_e32 v7, v0
	v_add_f32_e32 v4, v15, v4
	v_exp_f32_e32 v6, v6
	v_exp_f32_e32 v8, v8
	v_exp_f32_e32 v4, v4
	v_cvt_pk_bf16_f32 v0, v13, v20
	v_cvt_pk_bf16_f32 v3, v21, v7
	v_add_f32_e32 v9, v29, v38
	v_cvt_pk_bf16_f32 v38, v6, v8
	s_waitcnt vmcnt(11)
	v_mfma_f32_32x32x16_bf16 v[16:31], v[16:19], v[0:3], 0
	v_cvt_pk_bf16_f32 v41, v41, v4
	v_add_f32_e32 v10, v11, v10
	v_add_f32_e32 v11, v39, v40
	v_add_f32_e32 v9, v15, v9
	v_add_f32_e32 v10, v15, v10
	v_add_f32_e32 v11, v15, v11
	v_add_f32_e32 v12, v15, v12
	v_exp_f32_e32 v9, v9
	v_exp_f32_e32 v10, v10
	v_exp_f32_e32 v11, v11
	v_exp_f32_e32 v12, v12
	v_cvt_pk_bf16_f32 v39, v9, v10
	v_cvt_pk_bf16_f32 v40, v11, v12
	s_waitcnt vmcnt(10)
	s_nop 0
	v_mfma_f32_32x32x16_bf16 v[16:31], v[32:35], v[38:41], v[16:31]
	s_waitcnt vmcnt(9)
	v_mfma_f32_32x32x16_bf16 v[0:15], v[148:151], v[0:3], 0
	s_waitcnt vmcnt(8)
	v_mfma_f32_32x32x16_bf16 v[0:15], v[152:155], v[38:41], v[0:15]
	v_add_f32_e64 v32, v44, v42
	v_add_f32_e64 v33, v45, v43
	v_add_f32_e32 v32, v32, v33
	v_cmp_gt_f32_e32 vcc, s53, v32
	s_cmp_eq_u64 vcc, exec
	s_cselect_b64 s[56:57], -1, 0
	s_cmp_eq_u32 s42, 0
	s_cselect_b64 s[64:65], -1, 0
	s_or_b64 s[56:57], s[64:65], s[56:57]
	s_and_b64 vcc, exec, s[56:57]
	s_cbranch_vccnz .LBB0_109
	s_addk_i32 s94, 0x8000
	s_add_i32 s41, s42, 1
	s_add_i32 s42, s42, -1
	v_add_f32_e32 v103, 0, v32
	s_mov_b64 s[64:65], s[94:95]
	s_branch .LBB0_119

; #define MFMA32(a, b, c) __builtin_amdgcn_mfma_f32_32x32x16_bf16((a), (b), (c), 0, 0, 0)
; __device__ __forceinline__ void attn_unit(const bf16* Q, const bf16* Kb, const bf16* VT, bf16* OSB, int wu, int lane) {
;     ...
;         bf16x8 kn[4], vn[2][2];
;         { const int ktn = kt > 0 ? kt - 1 : 0; const bf16* kp = kbase + (size_t)ktn * 32 * 512; const bf16* vp = vbase + (size_t)ktn * (512 * 32);
; #pragma unroll
;           for (int kk = 0; kk < 4; ++kk) kn[kk] = *(const bf16x8*)(kp + kk * 16);
; #pragma unroll
;           for (int mt = 0; mt < 2; ++mt)
; #pragma unroll
;               for (int s = 0; s < 2; ++s) vn[mt][s] = *(const bf16x8*)(vp + mt * 32 * 32 + 16 * s); }
;         f32x16 sc;
; #pragma unroll
;         for (int i = 0; i < 16; ++i) sc[i] = 0.f;
; #pragma unroll
;         for (int kk = 0; kk < 4; ++kk) sc = MFMA32(kf[kk], qf[kk], sc);
;         const int lim = (kt == qblk) ? r : 64;
;         float ln[16], ls[16];
; #pragma unroll
;         for (int i = 0; i < 16; ++i) {
;             const float z = sc[i];
;             const float l2 = __builtin_amdgcn_logf(1.0f + __builtin_amdgcn_exp2f(-fabsf(z)));
;             const float sp = fmaxf(z, 0.f) + l2;
;             const bool valid = (16 * (i >> 3) + 8 * hh + (i & 7)) < lim;
;             ln[i] = valid ? -sp : 0.f;
;             ls[i] = valid ? z - sp : -1e30f;
;         }
.LBB0_119:
	s_sub_i32 s56, s64, 0x8000
	s_max_i32 s56, s56, 0
	s_mov_b32 s57, 0
	v_mov_b32_e32 v110, v179
	v_mov_b32_e32 v112, v179
	v_lshl_add_u64 v[156:157], v[98:99], 0, s[56:57]
	v_lshl_add_u64 v[158:159], v[100:101], 0, s[56:57]
	s_waitcnt vmcnt(4)
	v_mfma_f32_32x32x16_bf16 v[32:47], v[192:195], v[48:51], 0
	v_mfma_f32_32x32x16_bf16 v[32:47], v[196:199], v[52:55], v[32:47]
	v_mfma_f32_32x32x16_bf16 v[32:47], v[200:203], v[56:59], v[32:47]
	v_mfma_f32_32x32x16_bf16 v[32:47], v[204:207], v[60:63], v[32:47]
	global_load_dwordx4 v[192:195], v[156:157], off
	global_load_dwordx4 v[196:199], v[156:157], off offset:32
	global_load_dwordx4 v[200:203], v[156:157], off offset:64
	global_load_dwordx4 v[204:207], v[156:157], off offset:96
	s_nop 11
	v_exp_f32_e64 v87, -|v33|
	v_exp_f32_e64 v132, -|v38|
	v_exp_f32_e64 v133, -|v39|
	v_exp_f32_e64 v137, -|v43|
	v_exp_f32_e64 v138, -|v44|
	v_exp_f32_e64 v139, -|v45|
	v_exp_f32_e64 v140, -|v46|
	v_exp_f32_e64 v141, -|v47|
	v_exp_f32_e64 v75, -|v32|
	v_exp_f32_e64 v109, -|v35|
	v_exp_f32_e64 v130, -|v36|
	v_exp_f32_e64 v131, -|v37|
	v_exp_f32_e64 v136, -|v42|
	v_exp_f32_e64 v102, -|v34|
	v_exp_f32_e64 v134, -|v40|
	v_exp_f32_e64 v135, -|v41|
	v_max_f32_e32 v120, v38, v38
	v_max_f32_e32 v117, v35, v35
	v_mov_b32_e32 v111, v38
	v_mov_b32_e32 v38, v35
	v_max_f32_e32 v115, 0, v33
	v_max_f32_e32 v121, 0, v120
	v_max_f32_e32 v120, 0, v39
	v_max_f32_e32 v122, 0, v40
	v_max_f32_e32 v123, 0, v41
	v_max_f32_e32 v124, 0, v42
	v_max_f32_e32 v125, 0, v43
	v_max_f32_e32 v126, 0, v44
	v_max_f32_e32 v127, 0, v45
	v_max_f32_e32 v128, 0, v47
	v_add_f32_e32 v35, 1.0, v87
	v_add_f32_e32 v87, 1.0, v132
	v_add_f32_e32 v95, 1.0, v133
	v_add_f32_e32 v142, 1.0, v137
	v_add_f32_e32 v143, 1.0, v138
	v_add_f32_e32 v144, 1.0, v139
	v_add_f32_e32 v145, 1.0, v140
	v_add_f32_e32 v146, 1.0, v141
	v_max_f32_e32 v129, v46, v46
	v_mov_b32_e32 v106, v33
	v_mov_b32_e32 v113, v46
	v_mov_b32_e32 v46, v43
	v_max_f32_e32 v114, 0, v32
	v_add_f32_e32 v33, 1.0, v75
	v_add_f32_e32 v43, 1.0, v109
	v_add_f32_e32 v75, 1.0, v130
	v_add_f32_e32 v77, 1.0, v131
	v_add_f32_e32 v109, 1.0, v136
	v_log_f32_e32 v137, v87
	v_log_f32_e32 v136, v95
	v_log_f32_e32 v141, v142
	v_log_f32_e32 v142, v143
	v_log_f32_e32 v143, v144
	v_log_f32_e32 v145, v145
	v_log_f32_e32 v144, v146
	v_mov_b32_e32 v108, v41
	v_max_f32_e32 v116, 0, v34
	v_add_f32_e32 v41, 1.0, v102
	v_add_f32_e32 v102, 1.0, v134
	v_add_f32_e32 v107, 1.0, v135
	v_log_f32_e32 v134, v75
	v_log_f32_e32 v135, v77
	v_log_f32_e32 v130, v33
	v_log_f32_e32 v131, v35
	v_max_f32_e32 v129, 0, v129
	v_max_f32_e32 v118, 0, v36
	v_max_f32_e32 v119, 0, v37
	v_pk_add_f32 v[120:121], v[120:121], v[136:137]
	v_pk_add_f32 v[128:129], v[128:129], v[144:145]
	v_log_f32_e32 v132, v41
	v_log_f32_e32 v133, v43
	v_log_f32_e32 v140, v109
	v_pk_add_f32 v[118:119], v[118:119], v[134:135]
	v_pk_add_f32 v[126:127], v[126:127], v[142:143]
	v_pk_add_f32 v[110:111], v[110:111], v[120:121] neg_lo:[0,1] neg_hi:[0,1]
	v_pk_add_f32 v[112:113], v[112:113], v[128:129] neg_lo:[0,1] neg_hi:[0,1]
	v_log_f32_e32 v138, v102
	v_log_f32_e32 v139, v107
	v_pk_add_f32 v[114:115], v[114:115], v[130:131]
	v_sub_f32_e32 v130, v39, v120
	v_mov_b32_e32 v120, v119
	v_sub_f32_e32 v137, v47, v128
	v_mov_b32_e32 v128, v127
	v_pk_mov_b32 v[142:143], v[36:37], v[110:111] op_sel:[1,0]
	v_pk_mov_b32 v[144:145], v[44:45], v[112:113] op_sel:[1,0]
	v_pk_add_f32 v[120:121], v[142:143], v[120:121] neg_lo:[0,1] neg_hi:[0,1]
	v_pk_add_f32 v[128:129], v[144:145], v[128:129] neg_lo:[0,1] neg_hi:[0,1]
	v_max_f32_e32 v117, 0, v117
	v_mov_b32_e32 v37, v121
	v_mov_b32_e32 v45, v129
	v_pk_add_f32 v[116:117], v[116:117], v[132:133]
	v_pk_add_f32 v[124:125], v[124:125], v[140:141]
	v_pk_add_f32 v[36:37], v[36:37], v[118:119] neg_lo:[0,1] neg_hi:[0,1]
	v_pk_add_f32 v[44:45], v[44:45], v[126:127] neg_lo:[0,1] neg_hi:[0,1]
	v_pk_add_f32 v[122:123], v[122:123], v[138:139]
	v_pk_mov_b32 v[132:133], v[116:117], v[118:119] op_sel:[1,0]
	v_pk_mov_b32 v[138:139], v[124:125], v[126:127] op_sel:[1,0]
	v_mov_b32_e32 v39, v37
	v_mov_b32_e32 v47, v45
	v_pk_add_f32 v[38:39], v[38:39], v[132:133] neg_lo:[0,1] neg_hi:[0,1]
	v_pk_add_f32 v[46:47], v[46:47], v[138:139] neg_lo:[0,1] neg_hi:[0,1]
	v_mov_b32_e32 v35, v39
	v_mov_b32_e32 v43, v47
	v_pk_add_f32 v[34:35], v[34:35], v[116:117] neg_lo:[0,1] neg_hi:[0,1]
	v_pk_add_f32 v[42:43], v[42:43], v[124:125] neg_lo:[0,1] neg_hi:[0,1]
	v_pk_mov_b32 v[134:135], v[114:115], v[116:117] op_sel:[1,0]
	v_pk_mov_b32 v[140:141], v[122:123], v[124:125] op_sel:[1,0]
	v_mov_b32_e32 v107, v35
	v_mov_b32_e32 v109, v43
	v_pk_add_f32 v[106:107], v[106:107], v[134:135] neg_lo:[0,1] neg_hi:[0,1]
	v_pk_add_f32 v[108:109], v[108:109], v[140:141] neg_lo:[0,1] neg_hi:[0,1]
	v_mov_b32_e32 v33, v107
	v_mov_b32_e32 v41, v109
	v_pk_add_f32 v[32:33], v[32:33], v[114:115] neg_lo:[0,1] neg_hi:[0,1]
	v_pk_add_f32 v[40:41], v[40:41], v[122:123] neg_lo:[0,1] neg_hi:[0,1]
	v_pk_add_f32 v[114:115], v[32:33], v[114:115] op_sel:[1,0] op_sel_hi:[0,1] neg_lo:[0,1] neg_hi:[0,1]
	v_pk_add_f32 v[116:117], v[40:41], v[122:123] op_sel:[1,0] op_sel_hi:[0,1] neg_lo:[0,1] neg_hi:[0,1]
	ds_bpermute_b32 v118, v73, v116
	ds_bpermute_b32 v122, v73, v114
	v_mov_b32_e32 v102, v179
	v_add_f32_e32 v32, v32, v33
	v_add_f32_e32 v33, v106, v107
	s_waitcnt lgkmcnt(1)
; #define MFMA32(a, b, c) __builtin_amdgcn_mfma_f32_32x32x16_bf16((a), (b), (c), 0, 0, 0)
; __device__ __forceinline__ void attn_unit(const bf16* Q, const bf16* Kb, const bf16* VT, bf16* OSB, int wu, int lane) {
;     ...
;         float ex[16], gs[2];
; #pragma unroll
;         for (int s = 0; s < 2; ++s) { float run = 0.f;
; #pragma unroll
;             for (int j = 7; j >= 0; --j) { ex[8 * s + j] = run; run += ln[8 * s + j]; }
;             gs[s] = run; }
;         const float pg0 = __shfl_xor(gs[0], 32), pg1 = __shfl_xor(gs[1], 32);
;         const float off1 = (hh == 0 ? pg1 : 0.f) + carry;
;         const float off0 = gs[1] + pg1 + (hh == 0 ? pg0 : 0.f) + carry;
;         float a0[8], a1[8];
; #pragma unroll
;         for (int j = 0; j < 8; ++j) { a0[j] = __builtin_amdgcn_exp2f(ls[j] + ex[j] + off0); a1[j] = __builtin_amdgcn_exp2f(ls[8 + j] + ex[8 + j] + off1); }
;         const bf16x8 p0 = pack8(a0), p1 = pack8(a1);
;         o0 = MFMA32(vf[0][0], p0, o0); o0 = MFMA32(vf[0][1], p1, o0);
;         o1 = MFMA32(vf[1][0], p0, o1); o1 = MFMA32(vf[1][1], p1, o1);
;         carry += (gs[0] + gs[1]) + (pg0 + pg1);
;         if (__all(carry < -60.f)) break;
; #pragma unroll
;         for (int kk = 0; kk < 4; ++kk) kf[kk] = kn[kk];
; #pragma unroll
;         for (int mt = 0; mt < 2; ++mt)
; #pragma unroll
;             for (int s = 0; s < 2; ++s) vf[mt][s] = vn[mt][s];
	v_add_f32_e32 v75, v116, v118
	s_waitcnt lgkmcnt(0)
	v_cndmask_b32_e64 v77, v122, 0, s[4:5]
	v_add_f32_e32 v131, v77, v75
	v_pk_add_f32 v[124:125], v[102:103], v[130:131]
	v_add_f32_e32 v34, v34, v35
	v_add_f32_e32 v35, v38, v39
	v_add_f32_e32 v36, v36, v37
	v_add_f32_e32 v37, v120, v121
	v_add_f32_e32 v38, v110, v111
	v_add_f32_e32 v32, v32, v125
	v_add_f32_e32 v33, v33, v125
	v_add_f32_e32 v34, v34, v125
	v_add_f32_e32 v35, v35, v125
	v_add_f32_e32 v36, v36, v125
	v_add_f32_e32 v37, v37, v125
	v_add_f32_e32 v38, v38, v125
	v_add_f32_e32 v39, v124, v125
	v_exp_f32_e32 v32, v32
	v_exp_f32_e32 v33, v33
	v_exp_f32_e32 v34, v34
	v_exp_f32_e32 v35, v35
	v_exp_f32_e32 v36, v36
	v_exp_f32_e32 v37, v37
	v_exp_f32_e32 v38, v38
	v_exp_f32_e32 v39, v39
	v_cvt_pk_bf16_f32 v32, v32, v33
	v_cvt_pk_bf16_f32 v33, v34, v35
	v_cvt_pk_bf16_f32 v34, v36, v37
	v_cvt_pk_bf16_f32 v35, v38, v39
	v_cndmask_b32_e64 v178, v118, 0, s[4:5]
	v_mov_b32_e32 v136, v103
	v_pk_add_f32 v[106:107], v[136:137], v[178:179]
	v_add_f32_e32 v40, v40, v41
	v_add_f32_e32 v41, v108, v109
	v_add_f32_e32 v42, v42, v43
	v_add_f32_e32 v43, v46, v47
	v_add_f32_e32 v44, v44, v45
	v_add_f32_e32 v45, v128, v129
	v_add_f32_e32 v46, v112, v113
	v_add_f32_e32 v40, v106, v40
	v_add_f32_e32 v41, v106, v41
	v_add_f32_e32 v42, v106, v42
	v_add_f32_e32 v43, v106, v43
	v_add_f32_e32 v44, v106, v44
	v_add_f32_e32 v45, v106, v45
	v_add_f32_e32 v46, v106, v46
	v_add_f32_e32 v47, v106, v107
	v_exp_f32_e32 v40, v40
	v_exp_f32_e32 v41, v41
	v_exp_f32_e32 v42, v42
	v_exp_f32_e32 v43, v43
	v_exp_f32_e32 v44, v44
	v_exp_f32_e32 v45, v45
	v_exp_f32_e32 v46, v46
	v_exp_f32_e32 v47, v47
	v_cvt_pk_bf16_f32 v40, v40, v41
	v_cvt_pk_bf16_f32 v41, v42, v43
	v_cvt_pk_bf16_f32 v42, v44, v45
	v_cvt_pk_bf16_f32 v43, v46, v47
	s_waitcnt vmcnt(4)
	v_mfma_f32_32x32x16_bf16 v[16:31], v[208:211], v[32:35], v[16:31]
	v_mov_b32_e32 v123, v114
	v_mov_b32_e32 v119, v116
	v_mfma_f32_32x32x16_bf16 v[0:15], v[216:219], v[32:35], v[0:15]
	v_add_f32_e64 v32, v122, v118
	v_add_f32_e64 v33, v123, v119
	v_add_f32_e32 v32, v32, v33
	v_add_f32_e32 v103, v103, v32
	v_cmp_gt_f32_e32 vcc, s53, v103
	s_cmp_eq_u64 vcc, exec
	s_mov_b64 vcc, -1
	v_mfma_f32_32x32x16_bf16 v[16:31], v[212:215], v[40:43], v[16:31]
	v_mfma_f32_32x32x16_bf16 v[0:15], v[220:223], v[40:43], v[0:15]
	global_load_dwordx4 v[208:211], v[158:159], off
	global_load_dwordx4 v[212:215], v[158:159], off offset:32
	global_load_dwordx4 v[216:219], v[158:159], off offset:2048
	global_load_dwordx4 v[220:223], v[158:159], off offset:2080
	s_cbranch_scc1 .LBB0_118
	s_min_u32 s43, s42, 1
	s_sub_i32 s43, s41, s43
	s_add_i32 s94, s43, -2
	s_lshl_b64 s[64:65], s[94:95], 15
	s_add_i32 s41, s41, -1
	s_add_i32 s42, s42, -1
	s_cmp_lt_u32 s41, 2
	s_cselect_b64 vcc, -1, 0
	s_branch .LBB0_118

; __device__ __forceinline__ unsigned pk2(float lo, float hi) { f32v2 v = {lo, hi}; bf16v2 r = __builtin_convertvector(v, bf16v2); return __builtin_bit_cast(unsigned, r); }
;     __device__ __forceinline__ void operator()(f32x4 (&acc)[2][2][4][2], const Unit& u, int wr, int wc, int fr, int fq) const {
;     ...
;         for (int ai = 0; ai < 2; ++ai)
; #pragma unroll
;             for (int m = 0; m < 4; ++m) {
;                 const size_t row = (size_t)(row0 + ai * HALF + m * 16);
; #pragma unroll
;                 for (int bj = 0; bj < 2; ++bj) {
;                     f32x4 v0 = acc[ai][bj][m][0], v1 = acc[ai][bj][m][1];
;                     const int cl = cl0 + bj * HALF;
;                     if constexpr (MODE == 0 || MODE == 1) {
;                         if (MODE == 1) {
; #pragma unroll
;                             for (int e = 0; e < 4; ++e) { const float a = fmaxf(v0[e], 0.f), b = fmaxf(v1[e], 0.f); v0[e] = a * a; v1[e] = b * b; }
;                         }
;                         u32x4 w; w.x = pk2(v0[0], v0[1]); w.y = pk2(v0[2], v0[3]); w.z = pk2(v1[0], v1[1]); w.w = pk2(v1[2], v1[3]);
;                         if constexpr (MODE == 1) __builtin_nontemporal_store(w, (u32x4*)(O + row * ldc + u.pn * BM + cl));
;                         else *(u32x4*)(O + row * ldc + u.pn * BM + cl) = w;
.LBB0_561:
	s_andn2_b64 vcc, exec, s[6:7]
	s_cbranch_vccnz .LBB0_563
	v_ashrrev_i32_e32 v147, 31, v146
	s_lshl_b32 s6, s70, 8
	v_lshlrev_b64 v[128:129], 13, v[146:147]
	v_max_f32_e32 v132, 0, v120
	v_max_f32_e32 v148, 0, v122
	s_ashr_i32 s7, s6, 31
	v_lshl_add_u64 v[128:129], s[92:93], 0, v[128:129]
	v_max_f32_e32 v130, 0, v124
	v_max_f32_e32 v131, 0, v125
	v_max_f32_e32 v133, 0, v121
	v_max_f32_e32 v134, 0, v126
	v_max_f32_e32 v135, 0, v127
	v_max_f32_e32 v149, 0, v123
	s_lshl_b64 s[6:7], s[6:7], 1
	v_pk_mul_f32 v[130:131], v[130:131], v[130:131]
	v_pk_mul_f32 v[132:133], v[132:133], v[132:133]
	v_pk_mul_f32 v[134:135], v[134:135], v[134:135]
	v_pk_mul_f32 v[148:149], v[148:149], v[148:149]
	v_lshl_add_u64 v[128:129], v[128:129], 0, s[6:7]
	v_lshlrev_b32_e32 v178, 1, v138
	v_cvt_pk_bf16_f32 v130, v130, v131
	v_cvt_pk_bf16_f32 v131, v134, v135
	v_cvt_pk_bf16_f32 v132, v132, v133
	v_cvt_pk_bf16_f32 v133, v148, v149
	v_lshl_add_u64 v[128:129], v[128:129], 0, v[178:179]
	global_store_dwordx4 v[128:129], v[130:133], off sc0 sc1 nt
	s_nop 1
	v_max_f32_e32 v132, 0, v112
	v_max_f32_e32 v148, 0, v114
	v_max_f32_e32 v130, 0, v116
	v_max_f32_e32 v131, 0, v117
	v_max_f32_e32 v133, 0, v113
	v_max_f32_e32 v134, 0, v118
	v_max_f32_e32 v135, 0, v119
	v_max_f32_e32 v149, 0, v115
	v_pk_mul_f32 v[130:131], v[130:131], v[130:131]
	v_pk_mul_f32 v[132:133], v[132:133], v[132:133]
	v_pk_mul_f32 v[134:135], v[134:135], v[134:135]
	v_pk_mul_f32 v[148:149], v[148:149], v[148:149]
	v_cvt_pk_bf16_f32 v130, v130, v131
	v_cvt_pk_bf16_f32 v131, v134, v135
	v_cvt_pk_bf16_f32 v132, v132, v133
	v_cvt_pk_bf16_f32 v133, v148, v149
	global_store_dwordx4 v[128:129], v[130:133], off offset:256 sc0 sc1 nt
	s_nop 1
	v_max_f32_e32 v148, 0, v110
	v_or_b32_e32 v130, 16, v146
	v_ashrrev_i32_e32 v131, 31, v130
	v_lshlrev_b64 v[130:131], 13, v[130:131]
	v_lshl_add_u64 v[134:135], s[92:93], 0, v[130:131]
	v_max_f32_e32 v150, 0, v106
	v_max_f32_e32 v132, 0, v104
	v_max_f32_e32 v149, 0, v111
	v_max_f32_e32 v130, 0, v108
	v_max_f32_e32 v131, 0, v109
	v_max_f32_e32 v133, 0, v105
	v_max_f32_e32 v151, 0, v107
	v_pk_mul_f32 v[130:131], v[130:131], v[130:131]
	v_pk_mul_f32 v[132:133], v[132:133], v[132:133]
	v_pk_mul_f32 v[148:149], v[148:149], v[148:149]
	v_pk_mul_f32 v[150:151], v[150:151], v[150:151]
	v_lshl_add_u64 v[134:135], v[134:135], 0, s[6:7]
	v_cvt_pk_bf16_f32 v130, v130, v131
	v_cvt_pk_bf16_f32 v131, v148, v149
	v_cvt_pk_bf16_f32 v132, v132, v133
	v_cvt_pk_bf16_f32 v133, v150, v151
	v_lshl_add_u64 v[134:135], v[134:135], 0, v[178:179]
	v_max_f32_e32 v148, 0, v102
	global_store_dwordx4 v[134:135], v[130:133], off sc0 sc1 nt
	s_nop 1
	v_max_f32_e32 v150, 0, v98
	v_max_f32_e32 v132, 0, v96
	v_max_f32_e32 v149, 0, v103
	v_max_f32_e32 v130, 0, v100
	v_max_f32_e32 v131, 0, v101
	v_max_f32_e32 v133, 0, v97
	v_max_f32_e32 v151, 0, v99
	v_pk_mul_f32 v[130:131], v[130:131], v[130:131]
	v_pk_mul_f32 v[132:133], v[132:133], v[132:133]
	v_pk_mul_f32 v[148:149], v[148:149], v[148:149]
	v_pk_mul_f32 v[150:151], v[150:151], v[150:151]
	v_cvt_pk_bf16_f32 v130, v130, v131
	v_cvt_pk_bf16_f32 v131, v148, v149
	v_cvt_pk_bf16_f32 v132, v132, v133
	v_cvt_pk_bf16_f32 v133, v150, v151
	global_store_dwordx4 v[134:135], v[130:133], off offset:256 sc0 sc1 nt
	s_nop 1
	v_max_f32_e32 v148, 0, v94
	v_or_b32_e32 v130, 32, v146
	v_ashrrev_i32_e32 v131, 31, v130
	v_lshlrev_b64 v[130:131], 13, v[130:131]
	v_lshl_add_u64 v[134:135], s[92:93], 0, v[130:131]
	v_max_f32_e32 v150, 0, v90
	v_max_f32_e32 v132, 0, v88
	v_max_f32_e32 v149, 0, v95
	v_max_f32_e32 v130, 0, v92
	v_max_f32_e32 v131, 0, v93
	v_max_f32_e32 v133, 0, v89
	v_max_f32_e32 v151, 0, v91
	v_pk_mul_f32 v[130:131], v[130:131], v[130:131]
	v_pk_mul_f32 v[132:133], v[132:133], v[132:133]
	v_pk_mul_f32 v[148:149], v[148:149], v[148:149]
	v_pk_mul_f32 v[150:151], v[150:151], v[150:151]
	v_lshl_add_u64 v[134:135], v[134:135], 0, s[6:7]
	v_cvt_pk_bf16_f32 v130, v130, v131
	v_cvt_pk_bf16_f32 v131, v148, v149
	v_cvt_pk_bf16_f32 v132, v132, v133
	v_cvt_pk_bf16_f32 v133, v150, v151
	v_lshl_add_u64 v[134:135], v[134:135], 0, v[178:179]
	v_max_f32_e32 v148, 0, v86
	global_store_dwordx4 v[134:135], v[130:133], off sc0 sc1 nt
	s_nop 1
	v_max_f32_e32 v150, 0, v82
	v_max_f32_e32 v132, 0, v80
	v_max_f32_e32 v149, 0, v87
	v_max_f32_e32 v130, 0, v84
	v_max_f32_e32 v131, 0, v85
	v_max_f32_e32 v133, 0, v81
	v_max_f32_e32 v151, 0, v83
	v_pk_mul_f32 v[130:131], v[130:131], v[130:131]
	v_pk_mul_f32 v[132:133], v[132:133], v[132:133]
	v_pk_mul_f32 v[148:149], v[148:149], v[148:149]
	v_pk_mul_f32 v[150:151], v[150:151], v[150:151]
	v_cvt_pk_bf16_f32 v130, v130, v131
	v_cvt_pk_bf16_f32 v131, v148, v149
	v_cvt_pk_bf16_f32 v132, v132, v133
	v_cvt_pk_bf16_f32 v133, v150, v151
	global_store_dwordx4 v[134:135], v[130:133], off offset:256 sc0 sc1 nt
	s_nop 1
	v_max_f32_e32 v148, 0, v78
	v_or_b32_e32 v130, 48, v146
	v_ashrrev_i32_e32 v131, 31, v130
	v_lshlrev_b64 v[130:131], 13, v[130:131]
	v_lshl_add_u64 v[134:135], s[92:93], 0, v[130:131]
	v_max_f32_e32 v150, 0, v74
	v_max_f32_e32 v132, 0, v72
	v_max_f32_e32 v149, 0, v79
	v_max_f32_e32 v130, 0, v76
	v_max_f32_e32 v131, 0, v77
	v_max_f32_e32 v133, 0, v73
	v_max_f32_e32 v151, 0, v75
	v_pk_mul_f32 v[130:131], v[130:131], v[130:131]
	v_pk_mul_f32 v[132:133], v[132:133], v[132:133]
	v_pk_mul_f32 v[148:149], v[148:149], v[148:149]
	v_pk_mul_f32 v[150:151], v[150:151], v[150:151]
	v_lshl_add_u64 v[134:135], v[134:135], 0, s[6:7]
	v_cvt_pk_bf16_f32 v130, v130, v131
	v_cvt_pk_bf16_f32 v131, v148, v149
	v_cvt_pk_bf16_f32 v132, v132, v133
	v_cvt_pk_bf16_f32 v133, v150, v151
	v_lshl_add_u64 v[134:135], v[134:135], 0, v[178:179]
	v_max_f32_e32 v148, 0, v70
; __device__ __forceinline__ unsigned pk2(float lo, float hi) { f32v2 v = {lo, hi}; bf16v2 r = __builtin_convertvector(v, bf16v2); return __builtin_bit_cast(unsigned, r); }
;     __device__ __forceinline__ void operator()(f32x4 (&acc)[2][2][4][2], const Unit& u, int wr, int wc, int fr, int fq) const {
;     ...
;         for (int ai = 0; ai < 2; ++ai)
; #pragma unroll
;             for (int m = 0; m < 4; ++m) {
;                 const size_t row = (size_t)(row0 + ai * HALF + m * 16);
; #pragma unroll
;                 for (int bj = 0; bj < 2; ++bj) {
;                     f32x4 v0 = acc[ai][bj][m][0], v1 = acc[ai][bj][m][1];
;                     const int cl = cl0 + bj * HALF;
;                     if constexpr (MODE == 0 || MODE == 1) {
;                         if (MODE == 1) {
; #pragma unroll
;                             for (int e = 0; e < 4; ++e) { const float a = fmaxf(v0[e], 0.f), b = fmaxf(v1[e], 0.f); v0[e] = a * a; v1[e] = b * b; }
;                         }
;                         u32x4 w; w.x = pk2(v0[0], v0[1]); w.y = pk2(v0[2], v0[3]); w.z = pk2(v1[0], v1[1]); w.w = pk2(v1[2], v1[3]);
;                         if constexpr (MODE == 1) __builtin_nontemporal_store(w, (u32x4*)(O + row * ldc + u.pn * BM + cl));
;                         else *(u32x4*)(O + row * ldc + u.pn * BM + cl) = w;
	global_store_dwordx4 v[134:135], v[130:133], off sc0 sc1 nt
	s_nop 1
	v_max_f32_e32 v150, 0, v66
	v_max_f32_e32 v132, 0, v64
	v_max_f32_e32 v149, 0, v71
	v_max_f32_e32 v130, 0, v68
	v_max_f32_e32 v131, 0, v69
	v_max_f32_e32 v133, 0, v65
	v_max_f32_e32 v151, 0, v67
	v_pk_mul_f32 v[130:131], v[130:131], v[130:131]
	v_pk_mul_f32 v[132:133], v[132:133], v[132:133]
	v_pk_mul_f32 v[148:149], v[148:149], v[148:149]
	v_pk_mul_f32 v[150:151], v[150:151], v[150:151]
	v_cvt_pk_bf16_f32 v130, v130, v131
	v_cvt_pk_bf16_f32 v131, v148, v149
	v_cvt_pk_bf16_f32 v132, v132, v133
	v_cvt_pk_bf16_f32 v133, v150, v151
	global_store_dwordx4 v[134:135], v[130:133], off offset:256 sc0 sc1 nt
	s_nop 1
	v_max_f32_e32 v132, 0, v56
	v_max_f32_e32 v148, 0, v58
	v_max_f32_e32 v130, 0, v60
	v_max_f32_e32 v131, 0, v61
	v_max_f32_e32 v134, 0, v62
	v_max_f32_e32 v135, 0, v63
	v_max_f32_e32 v133, 0, v57
	v_pk_mul_f32 v[130:131], v[130:131], v[130:131]
	v_max_f32_e32 v149, 0, v59
	v_pk_mul_f32 v[134:135], v[134:135], v[134:135]
	s_mov_b64 s[6:7], 0x100000
	v_pk_mul_f32 v[132:133], v[132:133], v[132:133]
	v_pk_mul_f32 v[148:149], v[148:149], v[148:149]
	v_cvt_pk_bf16_f32 v130, v130, v131
	v_cvt_pk_bf16_f32 v131, v134, v135
	v_lshl_add_u64 v[134:135], v[128:129], 0, s[6:7]
	s_mov_b32 s6, 0x100000
	v_cvt_pk_bf16_f32 v132, v132, v133
	v_cvt_pk_bf16_f32 v133, v148, v149
	v_add_co_u32_e32 v148, vcc, s6, v128
	s_nop 0
	v_addc_co_u32_e32 v149, vcc, 0, v129, vcc
	global_store_dwordx4 v[148:149], v[130:133], off sc0 sc1 nt
	v_max_f32_e32 v148, 0, v54
	v_max_f32_e32 v150, 0, v50
	v_max_f32_e32 v132, 0, v48
	v_max_f32_e32 v149, 0, v55
	v_max_f32_e32 v130, 0, v52
	v_max_f32_e32 v131, 0, v53
	v_max_f32_e32 v133, 0, v49
	v_max_f32_e32 v151, 0, v51
	v_pk_mul_f32 v[130:131], v[130:131], v[130:131]
	v_pk_mul_f32 v[132:133], v[132:133], v[132:133]
	v_pk_mul_f32 v[148:149], v[148:149], v[148:149]
	v_pk_mul_f32 v[150:151], v[150:151], v[150:151]
	v_cvt_pk_bf16_f32 v130, v130, v131
	v_cvt_pk_bf16_f32 v131, v148, v149
	v_cvt_pk_bf16_f32 v132, v132, v133
	v_cvt_pk_bf16_f32 v133, v150, v151
	global_store_dwordx4 v[134:135], v[130:133], off offset:256 sc0 sc1 nt
	s_nop 1
	v_max_f32_e32 v132, 0, v40
	v_max_f32_e32 v148, 0, v42
	v_max_f32_e32 v130, 0, v44
	v_max_f32_e32 v131, 0, v45
	v_max_f32_e32 v134, 0, v46
	v_max_f32_e32 v135, 0, v47
	v_max_f32_e32 v133, 0, v41
	v_pk_mul_f32 v[130:131], v[130:131], v[130:131]
	v_max_f32_e32 v149, 0, v43
	v_pk_mul_f32 v[134:135], v[134:135], v[134:135]
	s_mov_b64 s[6:7], 0x120000
	v_pk_mul_f32 v[132:133], v[132:133], v[132:133]
	v_pk_mul_f32 v[148:149], v[148:149], v[148:149]
	v_cvt_pk_bf16_f32 v130, v130, v131
	v_cvt_pk_bf16_f32 v131, v134, v135
	v_lshl_add_u64 v[134:135], v[128:129], 0, s[6:7]
	s_mov_b32 s6, 0x120000
	v_cvt_pk_bf16_f32 v132, v132, v133
	v_cvt_pk_bf16_f32 v133, v148, v149
	v_add_co_u32_e32 v148, vcc, s6, v128
	s_nop 0
	v_addc_co_u32_e32 v149, vcc, 0, v129, vcc
	global_store_dwordx4 v[148:149], v[130:133], off sc0 sc1 nt
	v_max_f32_e32 v148, 0, v38
	v_max_f32_e32 v150, 0, v34
	v_max_f32_e32 v132, 0, v32
	v_max_f32_e32 v149, 0, v39
	v_max_f32_e32 v130, 0, v36
	v_max_f32_e32 v131, 0, v37
	v_max_f32_e32 v133, 0, v33
	v_max_f32_e32 v151, 0, v35
	v_pk_mul_f32 v[130:131], v[130:131], v[130:131]
	v_pk_mul_f32 v[132:133], v[132:133], v[132:133]
	v_pk_mul_f32 v[148:149], v[148:149], v[148:149]
	v_pk_mul_f32 v[150:151], v[150:151], v[150:151]
	v_cvt_pk_bf16_f32 v130, v130, v131
	v_cvt_pk_bf16_f32 v131, v148, v149
	v_cvt_pk_bf16_f32 v132, v132, v133
	v_cvt_pk_bf16_f32 v133, v150, v151
	global_store_dwordx4 v[134:135], v[130:133], off offset:256 sc0 sc1 nt
	s_nop 1
	v_max_f32_e32 v132, 0, v24
	v_max_f32_e32 v148, 0, v26
	v_max_f32_e32 v130, 0, v28
	v_max_f32_e32 v131, 0, v29
	v_max_f32_e32 v134, 0, v30
	v_max_f32_e32 v135, 0, v31
	v_max_f32_e32 v133, 0, v25
	v_pk_mul_f32 v[130:131], v[130:131], v[130:131]
	v_max_f32_e32 v149, 0, v27
	v_pk_mul_f32 v[134:135], v[134:135], v[134:135]
	s_mov_b64 s[6:7], 0x140000
	v_pk_mul_f32 v[132:133], v[132:133], v[132:133]
	v_pk_mul_f32 v[148:149], v[148:149], v[148:149]
	v_cvt_pk_bf16_f32 v130, v130, v131
	v_cvt_pk_bf16_f32 v131, v134, v135
	v_lshl_add_u64 v[134:135], v[128:129], 0, s[6:7]
	s_mov_b32 s6, 0x140000
	v_cvt_pk_bf16_f32 v132, v132, v133
	v_cvt_pk_bf16_f32 v133, v148, v149
	v_add_co_u32_e32 v148, vcc, s6, v128
	s_nop 0
	v_addc_co_u32_e32 v149, vcc, 0, v129, vcc
	global_store_dwordx4 v[148:149], v[130:133], off sc0 sc1 nt
	v_max_f32_e32 v148, 0, v22
	v_max_f32_e32 v150, 0, v18
	v_max_f32_e32 v132, 0, v16
	v_max_f32_e32 v149, 0, v23
	v_max_f32_e32 v130, 0, v20
	v_max_f32_e32 v131, 0, v21
	v_max_f32_e32 v133, 0, v17
	v_max_f32_e32 v151, 0, v19
	v_pk_mul_f32 v[130:131], v[130:131], v[130:131]
	v_pk_mul_f32 v[132:133], v[132:133], v[132:133]
	v_pk_mul_f32 v[148:149], v[148:149], v[148:149]
	v_pk_mul_f32 v[150:151], v[150:151], v[150:151]
	v_cvt_pk_bf16_f32 v130, v130, v131
	v_cvt_pk_bf16_f32 v131, v148, v149
	v_cvt_pk_bf16_f32 v132, v132, v133
	v_cvt_pk_bf16_f32 v133, v150, v151
	global_store_dwordx4 v[134:135], v[130:133], off offset:256 sc0 sc1 nt
	s_nop 1
	v_max_f32_e32 v132, 0, v8
	v_max_f32_e32 v148, 0, v10
	v_max_f32_e32 v130, 0, v12
	v_max_f32_e32 v131, 0, v13
	v_max_f32_e32 v134, 0, v14
	v_max_f32_e32 v135, 0, v15
	v_pk_mul_f32 v[130:131], v[130:131], v[130:131]
	v_pk_mul_f32 v[134:135], v[134:135], v[134:135]
	s_mov_b64 s[6:7], 0x160000
	v_max_f32_e32 v133, 0, v9
	v_max_f32_e32 v149, 0, v11
	v_cvt_pk_bf16_f32 v130, v130, v131
	v_cvt_pk_bf16_f32 v131, v134, v135
	v_lshl_add_u64 v[134:135], v[128:129], 0, s[6:7]
	s_mov_b32 s6, 0x160000
	v_pk_mul_f32 v[132:133], v[132:133], v[132:133]
	v_pk_mul_f32 v[148:149], v[148:149], v[148:149]
	v_add_co_u32_e32 v128, vcc, s6, v128
	v_cvt_pk_bf16_f32 v132, v132, v133
	v_cvt_pk_bf16_f32 v133, v148, v149
	v_addc_co_u32_e32 v129, vcc, 0, v129, vcc
	global_store_dwordx4 v[128:129], v[130:133], off sc0 sc1 nt
	s_nop 1
	v_max_f32_e32 v130, 0, v0
	v_max_f32_e32 v148, 0, v2
	v_max_f32_e32 v147, v3, v3
	v_max_f32_e32 v128, 0, v4
	v_max_f32_e32 v129, 0, v5
	v_max_f32_e32 v131, 0, v1
	v_max_f32_e32 v132, 0, v6
	v_max_f32_e32 v133, 0, v7
	v_max_f32_e32 v149, 0, v147
	v_pk_mul_f32 v[128:129], v[128:129], v[128:129]
	v_pk_mul_f32 v[130:131], v[130:131], v[130:131]
	v_pk_mul_f32 v[132:133], v[132:133], v[132:133]
	v_pk_mul_f32 v[148:149], v[148:149], v[148:149]
	v_cvt_pk_bf16_f32 v128, v128, v129
	v_cvt_pk_bf16_f32 v129, v132, v133
	v_cvt_pk_bf16_f32 v130, v130, v131
	v_cvt_pk_bf16_f32 v131, v148, v149
	global_store_dwordx4 v[134:135], v[128:131], off offset:256 sc0 sc1 nt
